# DMA pieces of the next tile issued between the QK/PV MFMAs of stages 1-2 (copies 0-2) instead of at the loop top
# speedup vs baseline: 1.0333x; 1.0005x over previous
.LBB0_1340:
	s_add_u32 s20, s20, 0x20000
	s_addc_u32 s21, s21, 0
	s_add_u32 s22, s22, 0x2000
	s_addc_u32 s23, s23, 0
	s_add_u32 s24, s24, 0x80
	s_addc_u32 s25, s25, 0
	s_add_i32 s4, s97, 94
	s_cmp_gt_i32 s33, s4
	s_cbranch_scc1 .Lat_idle0
	ds_read_b128 v[202:205], v128
	ds_read_b128 v[206:209], v129
	ds_read_b128 v[210:213], v130
	ds_read_b128 v[214:217], v131
	ds_read_b128 v[218:221], v132
	ds_read_b128 v[222:225], v133
	v_exp_f32_e32 v64, v64
	v_exp_f32_e32 v65, v65
	v_add_f32_e32 v200, v200, v64
	v_exp_f32_e32 v66, v66
	s_waitcnt lgkmcnt(4)
	v_mfma_f32_32x32x16_bf16 v[80:95], v[202:205], v[96:99], v[230:245]
	ds_read_b128 v[202:205], v134
	v_add_f32_e32 v200, v200, v65
	v_exp_f32_e32 v67, v67
	v_add_f32_e32 v200, v200, v66
	v_mfma_f32_32x32x16_bf16 v[80:95], v[206:209], v[100:103], v[80:95]
	ds_read_b128 v[206:209], v135
	v_exp_f32_e32 v68, v68
	v_add_f32_e32 v200, v200, v67
	v_exp_f32_e32 v69, v69
	s_add_i32 m0, s52, 0x4000
	s_waitcnt lgkmcnt(4)
	v_mfma_f32_32x32x16_bf16 v[80:95], v[210:213], v[104:107], v[80:95]
	ds_read_b128 v[210:213], v136
	v_add_f32_e32 v200, v200, v68
	v_exp_f32_e32 v70, v70
	v_add_f32_e32 v200, v200, v69
	global_load_lds_dwordx4 v201, s[20:21]
	v_mfma_f32_32x32x16_bf16 v[80:95], v[214:217], v[108:111], v[80:95]
	ds_read_b128 v[214:217], v137
	v_exp_f32_e32 v71, v71
	v_add_f32_e32 v200, v200, v70
	v_exp_f32_e32 v72, v72
	s_waitcnt lgkmcnt(4)
	v_mfma_f32_32x32x16_bf16 v[80:95], v[218:221], v[112:115], v[80:95]
	ds_read_b128 v[218:221], v138
	v_add_f32_e32 v200, v200, v71
	v_exp_f32_e32 v73, v73
	v_add_f32_e32 v200, v200, v72
	s_add_i32 m0, s52, 0x6000
	v_mfma_f32_32x32x16_bf16 v[80:95], v[222:225], v[116:119], v[80:95]
	ds_read_b128 v[222:225], v139
	v_exp_f32_e32 v74, v74
	v_add_f32_e32 v200, v200, v73
	v_exp_f32_e32 v75, v75
	global_load_lds_dwordx4 v187, s[20:21]
	s_waitcnt lgkmcnt(4)
	v_mfma_f32_32x32x16_bf16 v[80:95], v[202:205], v[120:123], v[80:95]
	ds_read_b128 v[164:167], v144 offset:49152
	v_add_f32_e32 v200, v200, v74
	v_exp_f32_e32 v76, v76
	v_add_f32_e32 v200, v200, v75
	v_mfma_f32_32x32x16_bf16 v[80:95], v[206:209], v[124:127], v[80:95]
	ds_read_b128 v[168:171], v144 offset:53248
	v_exp_f32_e32 v77, v77
	v_add_f32_e32 v200, v200, v76
	v_exp_f32_e32 v78, v78
	s_add_i32 m0, s52, 0xa000
	s_waitcnt lgkmcnt(4)
	v_mfma_f32_32x32x16_bf16 v[80:95], v[210:213], v[160:163], v[80:95]
	ds_read_b128 v[176:179], v144 offset:57344
	v_add_f32_e32 v200, v200, v77
	v_exp_f32_e32 v79, v79
	v_add_f32_e32 v200, v200, v78
	global_load_lds_dwordx4 v189, s[22:23]
	v_mfma_f32_32x32x16_bf16 v[80:95], v[214:217], v[152:155], v[80:95]
	ds_read_b128 v[226:229], v144 offset:61440
	v_add_f32_e32 v200, v200, v79
	v_cvt_pk_bf16_f32 v64, v64, v65
	v_cvt_pk_bf16_f32 v65, v66, v67
	s_waitcnt lgkmcnt(4)
	v_mfma_f32_32x32x16_bf16 v[80:95], v[218:221], v[156:159], v[80:95]
	v_cvt_pk_bf16_f32 v66, v68, v69
	v_cvt_pk_bf16_f32 v67, v70, v71
	v_cvt_pk_bf16_f32 v68, v72, v73
	v_mfma_f32_32x32x16_bf16 v[80:95], v[222:225], v[148:151], v[80:95]
	v_cvt_pk_bf16_f32 v69, v74, v75
	v_cvt_pk_bf16_f32 v70, v76, v77
	v_cvt_pk_bf16_f32 v71, v78, v79
	s_waitcnt lgkmcnt(2)
	v_mfma_f32_32x32x16_bf16 v[48:63], v[164:167], v[64:67], v[48:63]
	ds_read_b128 v[164:167], v145 offset:49152
	s_add_i32 m0, s52, 0x10000
	v_mfma_f32_32x32x16_bf16 v[32:47], v[168:171], v[64:67], v[32:47]
	ds_read_b128 v[168:171], v145 offset:53248
	global_load_lds_dwordx4 v194, s[24:25]
	s_waitcnt lgkmcnt(2)
	v_mfma_f32_32x32x16_bf16 v[16:31], v[176:179], v[64:67], v[16:31]
	ds_read_b128 v[176:179], v145 offset:57344
	s_add_i32 m0, s52, 0x12000
	v_mfma_f32_32x32x16_bf16 v[0:15], v[226:229], v[64:67], v[0:15]
	ds_read_b128 v[226:229], v145 offset:61440
	global_load_lds_dwordx4 v195, s[24:25]
	ds_read_b128 v[202:205], v128 offset:8192
	ds_read_b128 v[206:209], v129 offset:8192
	ds_read_b128 v[210:213], v130 offset:8192
	ds_read_b128 v[214:217], v131 offset:8192
	ds_read_b128 v[218:221], v132 offset:8192
	ds_read_b128 v[222:225], v133 offset:8192
	s_cmp_gt_i32 s33, s97
	s_cbranch_scc1 .Lat_mask_a0

.Lat_copy1:
	s_add_u32 s20, s20, 0x20000
	s_addc_u32 s21, s21, 0
	s_add_u32 s22, s22, 0x2000
	s_addc_u32 s23, s23, 0
	s_add_u32 s24, s24, 0x80
	s_addc_u32 s25, s25, 0
	s_add_i32 s4, s97, 94
	s_cmp_gt_i32 s33, s4
	s_cbranch_scc1 .Lat_idle1
	ds_read_b128 v[202:205], v128 offset:16384
	ds_read_b128 v[206:209], v129 offset:16384
	ds_read_b128 v[210:213], v130 offset:16384
	ds_read_b128 v[214:217], v131 offset:16384
	ds_read_b128 v[218:221], v132 offset:16384
	ds_read_b128 v[222:225], v133 offset:16384
	v_exp_f32_e32 v64, v64
	v_exp_f32_e32 v65, v65
	v_add_f32_e32 v200, v200, v64
	v_exp_f32_e32 v66, v66
	s_waitcnt lgkmcnt(4)
	v_mfma_f32_32x32x16_bf16 v[80:95], v[202:205], v[96:99], v[230:245]
	ds_read_b128 v[202:205], v134 offset:16384
	v_add_f32_e32 v200, v200, v65
	v_exp_f32_e32 v67, v67
	v_add_f32_e32 v200, v200, v66
	v_mfma_f32_32x32x16_bf16 v[80:95], v[206:209], v[100:103], v[80:95]
	ds_read_b128 v[206:209], v135 offset:16384
	v_exp_f32_e32 v68, v68
	v_add_f32_e32 v200, v200, v67
	v_exp_f32_e32 v69, v69
	s_add_i32 m0, s52, 0x0
	s_waitcnt lgkmcnt(4)
	v_mfma_f32_32x32x16_bf16 v[80:95], v[210:213], v[104:107], v[80:95]
	ds_read_b128 v[210:213], v136 offset:8192
	v_add_f32_e32 v200, v200, v68
	v_exp_f32_e32 v70, v70
	v_add_f32_e32 v200, v200, v69
	global_load_lds_dwordx4 v201, s[20:21]
	v_mfma_f32_32x32x16_bf16 v[80:95], v[214:217], v[108:111], v[80:95]
	ds_read_b128 v[214:217], v137 offset:8192
	v_exp_f32_e32 v71, v71
	v_add_f32_e32 v200, v200, v70
	v_exp_f32_e32 v72, v72
	s_waitcnt lgkmcnt(4)
	v_mfma_f32_32x32x16_bf16 v[80:95], v[218:221], v[112:115], v[80:95]
	ds_read_b128 v[218:221], v138 offset:8192
	v_add_f32_e32 v200, v200, v71
	v_exp_f32_e32 v73, v73
	v_add_f32_e32 v200, v200, v72
	s_add_i32 m0, s52, 0x2000
	v_mfma_f32_32x32x16_bf16 v[80:95], v[222:225], v[116:119], v[80:95]
	ds_read_b128 v[222:225], v139 offset:8192
	v_exp_f32_e32 v74, v74
	v_add_f32_e32 v200, v200, v73
	v_exp_f32_e32 v75, v75
	global_load_lds_dwordx4 v187, s[20:21]
	s_waitcnt lgkmcnt(4)
	v_mfma_f32_32x32x16_bf16 v[80:95], v[202:205], v[120:123], v[80:95]
	ds_read_b128 v[164:167], v144
	v_add_f32_e32 v200, v200, v74
	v_exp_f32_e32 v76, v76
	v_add_f32_e32 v200, v200, v75
	v_mfma_f32_32x32x16_bf16 v[80:95], v[206:209], v[124:127], v[80:95]
	ds_read_b128 v[168:171], v144 offset:4096
	v_exp_f32_e32 v77, v77
	v_add_f32_e32 v200, v200, v76
	v_exp_f32_e32 v78, v78
	s_add_i32 m0, s52, 0x8000
	s_waitcnt lgkmcnt(4)
	v_mfma_f32_32x32x16_bf16 v[80:95], v[210:213], v[160:163], v[80:95]
	ds_read_b128 v[176:179], v144 offset:8192
	v_add_f32_e32 v200, v200, v77
	v_exp_f32_e32 v79, v79
	v_add_f32_e32 v200, v200, v78
	global_load_lds_dwordx4 v189, s[22:23]
	v_mfma_f32_32x32x16_bf16 v[80:95], v[214:217], v[152:155], v[80:95]
	ds_read_b128 v[226:229], v144 offset:12288
	v_add_f32_e32 v200, v200, v79
	v_cvt_pk_bf16_f32 v64, v64, v65
	v_cvt_pk_bf16_f32 v65, v66, v67
	s_waitcnt lgkmcnt(4)
	v_mfma_f32_32x32x16_bf16 v[80:95], v[218:221], v[156:159], v[80:95]
	v_cvt_pk_bf16_f32 v66, v68, v69
	v_cvt_pk_bf16_f32 v67, v70, v71
	v_cvt_pk_bf16_f32 v68, v72, v73
	v_mfma_f32_32x32x16_bf16 v[80:95], v[222:225], v[148:151], v[80:95]
	v_cvt_pk_bf16_f32 v69, v74, v75
	v_cvt_pk_bf16_f32 v70, v76, v77
	v_cvt_pk_bf16_f32 v71, v78, v79
	s_waitcnt lgkmcnt(2)
	v_mfma_f32_32x32x16_bf16 v[48:63], v[164:167], v[64:67], v[48:63]
	ds_read_b128 v[164:167], v145
	s_add_i32 m0, s52, 0x14000
	v_mfma_f32_32x32x16_bf16 v[32:47], v[168:171], v[64:67], v[32:47]
	ds_read_b128 v[168:171], v145 offset:4096
	global_load_lds_dwordx4 v194, s[24:25]
	s_waitcnt lgkmcnt(2)
	v_mfma_f32_32x32x16_bf16 v[16:31], v[176:179], v[64:67], v[16:31]
	ds_read_b128 v[176:179], v145 offset:8192
	s_add_i32 m0, s52, 0x16000
	v_mfma_f32_32x32x16_bf16 v[0:15], v[226:229], v[64:67], v[0:15]
	ds_read_b128 v[226:229], v145 offset:12288
	global_load_lds_dwordx4 v195, s[24:25]
	ds_read_b128 v[202:205], v128 offset:24576
	ds_read_b128 v[206:209], v129 offset:24576
	ds_read_b128 v[210:213], v130 offset:24576
	ds_read_b128 v[214:217], v131 offset:24576
	ds_read_b128 v[218:221], v132 offset:24576
	ds_read_b128 v[222:225], v133 offset:24576
	s_cmp_gt_i32 s33, s97
	s_cbranch_scc1 .Lat_mask_a1

.Lat_copy2:
	s_add_u32 s20, s20, 0x20000
	s_addc_u32 s21, s21, 0
	s_add_u32 s22, s22, 0x2000
	s_addc_u32 s23, s23, 0
	s_add_u32 s24, s24, 0x80
	s_addc_u32 s25, s25, 0
	s_add_i32 s4, s97, 94
	s_cmp_gt_i32 s33, s4
	s_cbranch_scc1 .Lat_idle2
	ds_read_b128 v[202:205], v128
	ds_read_b128 v[206:209], v129
	ds_read_b128 v[210:213], v130
	ds_read_b128 v[214:217], v131
	ds_read_b128 v[218:221], v132
	ds_read_b128 v[222:225], v133
	v_exp_f32_e32 v64, v64
	v_exp_f32_e32 v65, v65
	v_add_f32_e32 v200, v200, v64
	v_exp_f32_e32 v66, v66
	s_waitcnt lgkmcnt(4)
	v_mfma_f32_32x32x16_bf16 v[80:95], v[202:205], v[96:99], v[230:245]
	ds_read_b128 v[202:205], v134
	v_add_f32_e32 v200, v200, v65
	v_exp_f32_e32 v67, v67
	v_add_f32_e32 v200, v200, v66
	v_mfma_f32_32x32x16_bf16 v[80:95], v[206:209], v[100:103], v[80:95]
	ds_read_b128 v[206:209], v135
	v_exp_f32_e32 v68, v68
	v_add_f32_e32 v200, v200, v67
	v_exp_f32_e32 v69, v69
	s_add_i32 m0, s52, 0x4000
	s_waitcnt lgkmcnt(4)
	v_mfma_f32_32x32x16_bf16 v[80:95], v[210:213], v[104:107], v[80:95]
	ds_read_b128 v[210:213], v136
	v_add_f32_e32 v200, v200, v68
	v_exp_f32_e32 v70, v70
	v_add_f32_e32 v200, v200, v69
	global_load_lds_dwordx4 v201, s[20:21]
	v_mfma_f32_32x32x16_bf16 v[80:95], v[214:217], v[108:111], v[80:95]
	ds_read_b128 v[214:217], v137
	v_exp_f32_e32 v71, v71
	v_add_f32_e32 v200, v200, v70
	v_exp_f32_e32 v72, v72
	s_waitcnt lgkmcnt(4)
	v_mfma_f32_32x32x16_bf16 v[80:95], v[218:221], v[112:115], v[80:95]
	ds_read_b128 v[218:221], v138
	v_add_f32_e32 v200, v200, v71
	v_exp_f32_e32 v73, v73
	v_add_f32_e32 v200, v200, v72
	s_add_i32 m0, s52, 0x6000
	v_mfma_f32_32x32x16_bf16 v[80:95], v[222:225], v[116:119], v[80:95]
	ds_read_b128 v[222:225], v139
	v_exp_f32_e32 v74, v74
	v_add_f32_e32 v200, v200, v73
	v_exp_f32_e32 v75, v75
	global_load_lds_dwordx4 v187, s[20:21]
	s_waitcnt lgkmcnt(4)
	v_mfma_f32_32x32x16_bf16 v[80:95], v[202:205], v[120:123], v[80:95]
	ds_read_b128 v[164:167], v144 offset:16384
	v_add_f32_e32 v200, v200, v74
	v_exp_f32_e32 v76, v76
	v_add_f32_e32 v200, v200, v75
	v_mfma_f32_32x32x16_bf16 v[80:95], v[206:209], v[124:127], v[80:95]
	ds_read_b128 v[168:171], v144 offset:20480
	v_exp_f32_e32 v77, v77
	v_add_f32_e32 v200, v200, v76
	v_exp_f32_e32 v78, v78
	s_add_i32 m0, s52, 0xa000
	s_waitcnt lgkmcnt(4)
	v_mfma_f32_32x32x16_bf16 v[80:95], v[210:213], v[160:163], v[80:95]
	ds_read_b128 v[176:179], v144 offset:24576
	v_add_f32_e32 v200, v200, v77
	v_exp_f32_e32 v79, v79
	v_add_f32_e32 v200, v200, v78
	global_load_lds_dwordx4 v189, s[22:23]
	v_mfma_f32_32x32x16_bf16 v[80:95], v[214:217], v[152:155], v[80:95]
	ds_read_b128 v[226:229], v144 offset:28672
	v_add_f32_e32 v200, v200, v79
	v_cvt_pk_bf16_f32 v64, v64, v65
	v_cvt_pk_bf16_f32 v65, v66, v67
	s_waitcnt lgkmcnt(4)
	v_mfma_f32_32x32x16_bf16 v[80:95], v[218:221], v[156:159], v[80:95]
	v_cvt_pk_bf16_f32 v66, v68, v69
	v_cvt_pk_bf16_f32 v67, v70, v71
	v_cvt_pk_bf16_f32 v68, v72, v73
	v_mfma_f32_32x32x16_bf16 v[80:95], v[222:225], v[148:151], v[80:95]
	v_cvt_pk_bf16_f32 v69, v74, v75
	v_cvt_pk_bf16_f32 v70, v76, v77
	v_cvt_pk_bf16_f32 v71, v78, v79
	s_waitcnt lgkmcnt(2)
	v_mfma_f32_32x32x16_bf16 v[48:63], v[164:167], v[64:67], v[48:63]
	ds_read_b128 v[164:167], v145 offset:16384
	s_add_i32 m0, s52, 0x18000
	v_mfma_f32_32x32x16_bf16 v[32:47], v[168:171], v[64:67], v[32:47]
	ds_read_b128 v[168:171], v145 offset:20480
	global_load_lds_dwordx4 v194, s[24:25]
	s_waitcnt lgkmcnt(2)
	v_mfma_f32_32x32x16_bf16 v[16:31], v[176:179], v[64:67], v[16:31]
	ds_read_b128 v[176:179], v145 offset:24576
	s_add_i32 m0, s52, 0x1a000
	v_mfma_f32_32x32x16_bf16 v[0:15], v[226:229], v[64:67], v[0:15]
	ds_read_b128 v[226:229], v145 offset:28672
	global_load_lds_dwordx4 v195, s[24:25]
	ds_read_b128 v[202:205], v128 offset:8192
	ds_read_b128 v[206:209], v129 offset:8192
	ds_read_b128 v[210:213], v130 offset:8192
	ds_read_b128 v[214:217], v131 offset:8192
	ds_read_b128 v[218:221], v132 offset:8192
	ds_read_b128 v[222:225], v133 offset:8192
	s_cmp_gt_i32 s33, s97
	s_cbranch_scc1 .Lat_mask_a2

.Lat_idle_go0:
	s_add_i32 m0, s52, 0x4000
	s_nop 0
	global_load_lds_dwordx4 v201, s[20:21]
	s_add_i32 m0, s52, 0x6000
	s_nop 0
	global_load_lds_dwordx4 v187, s[20:21]
	s_add_i32 m0, s52, 0xa000
	s_nop 0
	global_load_lds_dwordx4 v189, s[22:23]
	s_add_i32 m0, s52, 0x10000
	s_nop 0
	global_load_lds_dwordx4 v194, s[24:25]
	s_add_i32 m0, s52, 0x12000
	s_nop 0
	global_load_lds_dwordx4 v195, s[24:25]
	s_branch .Lat_resc_b0_ret

.Lat_idle_go1:
	s_add_i32 m0, s52, 0x0
	s_nop 0
	global_load_lds_dwordx4 v201, s[20:21]
	s_add_i32 m0, s52, 0x2000
	s_nop 0
	global_load_lds_dwordx4 v187, s[20:21]
	s_add_i32 m0, s52, 0x8000
	s_nop 0
	global_load_lds_dwordx4 v189, s[22:23]
	s_add_i32 m0, s52, 0x14000
	s_nop 0
	global_load_lds_dwordx4 v194, s[24:25]
	s_add_i32 m0, s52, 0x16000
	s_nop 0
	global_load_lds_dwordx4 v195, s[24:25]
	s_branch .Lat_resc_b1_ret

.Lat_idle_go2:
	s_add_i32 m0, s52, 0x4000
	s_nop 0
	global_load_lds_dwordx4 v201, s[20:21]
	s_add_i32 m0, s52, 0x6000
	s_nop 0
	global_load_lds_dwordx4 v187, s[20:21]
	s_add_i32 m0, s52, 0xa000
	s_nop 0
	global_load_lds_dwordx4 v189, s[22:23]
	s_add_i32 m0, s52, 0x18000
	s_nop 0
	global_load_lds_dwordx4 v194, s[24:25]
	s_add_i32 m0, s52, 0x1a000
	s_nop 0
	global_load_lds_dwordx4 v195, s[24:25]
	s_branch .Lat_resc_b2_ret
